# ret_sample: item id reserved one item ahead (no atomic round trip / store drain between the item-top barriers) plus wave 0's A8 loop behind its first loads
# baseline (speedup 1.0000x reference)
.LBB0_1326:
	s_add_u32 s8, s94, 0x32c06000
	s_addc_u32 s9, s95, 0
	s_add_i32 s20, 0, 0x22fe0
	v_readlane_b32 s36, v254, 38
	v_readlane_b32 s38, v254, 42
	v_readlane_b32 s40, v254, 47
	v_readlane_b32 s42, v254, 59
	s_mov_b32 s11, 0
	v_mov_b32_e32 v153, 0
	v_mov_b32_e32 v200, s20
	s_movk_i32 s21, 0x1ff
	s_movk_i32 s22, 0x2000
	s_add_i32 s23, 0, 0x2000
	s_movk_i32 s24, 0x1000
	s_movk_i32 s25, 0x3000
	s_mov_b32 s26, 0x6d03000
	v_mov_b32_e32 v201, 0xbb80402b
	v_mov_b32_e32 v202, 0xbc0080ac
	v_mov_b32_e32 v203, 3
	v_mov_b32_e32 v204, 1
	v_readlane_b32 s37, v254, 39
	v_readlane_b32 s39, v254, 43
	v_readlane_b32 s41, v254, 48
	v_readlane_b32 s43, v254, 60
	v_cmp_eq_u32_e32 vcc, 0, v198
	s_nop 3
	s_and_saveexec_b64 s[0:1], vcc
	v_mov_b32_e32 v250, 1
	global_atomic_add v250, v153, v250, s[8:9] sc0
	s_waitcnt vmcnt(0)
	s_or_b64 exec, exec, s[0:1]
	s_branch .LBB0_1329

.LBB0_1329:
	v_mov_b32_e32 v152, v198
	s_nop 0
	v_cmp_eq_u32_e32 vcc, 0, v152
	s_barrier
	s_and_saveexec_b64 s[0:1], vcc
	s_cbranch_execz .LBB0_1333
	s_waitcnt vmcnt(31)
	v_mov_b32_e32 v1, s20
	ds_write_b32 v1, v250
	v_mov_b32_e32 v250, 1
	global_atomic_add v250, v153, v250, s[8:9] sc0
